# instruction selection: LDS-DMA address products as v_mul_u32_u24 instead of quarter-rate v_mul_lo_u32 in the mixer tile loops
# baseline (speedup 1.0000x reference)
; DI void ret_state_sweep(LAS unsigned char* lds, const bf16_t* MX, const bf16_t* VT, bf16_t* ST, int b, int hh, int dir, float lg, int wave) {
;     ...
;         if (it + 2 < 28) SW_ISSUE(it + 2, nx2);
.LBB0_135:
	s_barrier
	s_add_i32 s5, s38, -2
	s_cmp_gt_u32 s5, 25
	s_cbranch_scc1 .LBB0_137
	s_lshr_b32 s4, s38, 2
	v_readlane_b32 s14, v254, 18
	s_sub_i32 s11, 7, s4
	v_readlane_b32 s15, v254, 19
	s_and_b64 s[14:15], s[14:15], exec
	s_cselect_b32 s4, s4, s11
	s_lshl_b32 s4, s4, 2
	s_and_b32 s11, s38, 3
	v_mbcnt_lo_u32_b32 v64, -1, 0
	v_mbcnt_hi_u32_b32 v64, -1, v64
	s_or_b32 s62, s4, s11
	v_ashrrev_i32_e32 v65, 4, v64
	v_add_u32_e32 v66, s17, v65
	s_mul_i32 s11, s62, 0xa0000
	v_xor_b32_e32 v67, v66, v64
	s_mul_hi_u32 s4, s62, 0xa0000
	s_add_u32 s14, s8, s11
	v_lshlrev_b32_e32 v68, 4, v67
	v_lshlrev_b32_e32 v67, 3, v67
	s_addc_u32 s15, s9, s4
	s_mul_i32 s4, s10, 0xc000
	v_mul_u32_u24_e32 v66, s54, v66
	v_and_b32_e32 v68, 0x80, v68
	v_and_b32_e32 v67, 56, v67
	s_add_i32 s4, s4, 0
	v_or3_b32 v66, v68, v66, v67
	v_lshlrev_b32_e32 v66, 1, v66
	s_add_i32 m0, s4, s18
	v_add_u32_e32 v65, s19, v65
	global_load_lds_dwordx4 v66, s[14:15]
	v_xor_b32_e32 v66, v65, v64
	v_lshlrev_b32_e32 v67, 4, v66
	v_lshlrev_b32_e32 v66, 3, v66
	v_mul_u32_u24_e32 v65, s54, v65
	v_and_b32_e32 v67, 0x80, v67
	v_and_b32_e32 v66, 56, v66
	v_or3_b32 v65, v67, v65, v66
	v_lshlrev_b32_e32 v65, 1, v65
	s_add_i32 m0, s4, s24
	s_lshl_b64 s[28:29], s[62:63], 7
	global_load_lds_dwordx4 v65, s[14:15]
	v_ashrrev_i32_e32 v65, 3, v64
	v_lshrrev_b32_e32 v67, 1, v65
	v_add_u32_e32 v66, s3, v65
	v_xor_b32_e32 v67, v67, v64
	s_add_u32 s14, s6, s28
	v_mul_u32_u24_e32 v66, s0, v66
	v_lshlrev_b32_e32 v67, 3, v67
	s_addc_u32 s15, s7, s29
	v_and_or_b32 v66, v67, 56, v66
	s_add_i32 s11, s4, s30
	v_lshlrev_b32_e32 v66, 1, v66
	s_add_i32 m0, s11, 0x4000
	s_add_i32 s11, s4, s33
	global_load_lds_dwordx4 v66, s[14:15]
	v_add_u32_e32 v66, s31, v65
	v_lshrrev_b32_e32 v67, 1, v66
	v_xor_b32_e32 v67, v67, v64
	v_mul_u32_u24_e32 v66, s0, v66
	v_lshlrev_b32_e32 v67, 3, v67
	v_and_or_b32 v66, v67, 56, v66
	v_lshlrev_b32_e32 v66, 1, v66
	s_add_i32 m0, s11, 0x4000
	s_add_i32 s11, s4, s35
	global_load_lds_dwordx4 v66, s[14:15]
	v_add_u32_e32 v66, s34, v65
	v_lshrrev_b32_e32 v67, 1, v66
	v_xor_b32_e32 v67, v67, v64
	v_mul_u32_u24_e32 v66, s0, v66
	v_lshlrev_b32_e32 v67, 3, v67
	v_and_or_b32 v66, v67, 56, v66
	v_lshlrev_b32_e32 v66, 1, v66
	s_add_i32 m0, s11, 0x4000
	v_add_u32_e32 v65, s36, v65
	global_load_lds_dwordx4 v66, s[14:15]
	v_lshrrev_b32_e32 v66, 1, v65
	v_xor_b32_e32 v64, v66, v64
	v_mul_u32_u24_e32 v65, s0, v65
	v_lshlrev_b32_e32 v64, 3, v64
	v_and_or_b32 v64, v64, 56, v65
	s_add_i32 s4, s4, s37
	v_lshlrev_b32_e32 v64, 1, v64
	s_add_i32 m0, s4, 0x4000
	s_nop 0
	global_load_lds_dwordx4 v64, s[14:15]

; #define LAS __attribute__((address_space(3)))
; DI void ret_unit(LAS unsigned char* lds, bf16_t* MX, const bf16_t* VT, bf16_t* ST, int b, int hh, int qt, float lgf, float nlgb, int wave, const int mode) {
;     ...
;     if (mode == 0) {
;         tq = q0w + r;
;         const bf16_t* qrow = MX + (tok0 + tq) * MXW + C_RQ + qc + 8 * h;
; #pragma unroll
;         for (int s = 0; s < 8; ++s) qf[s] = *(const bf16x8*)(qrow + (s >> 2) * 128 + (s & 3) * 16);
;     } else {
;         tq = (wave < 4) ? qt * 256 + 255 : qt * 256;
;         const int target = 32 * (wave & 3) + r;
; #pragma unroll
;         for (int s = 0; s < 8; ++s) { const bool hit = ((target >> 4) == s) && (((target >> 3) & 1) == h); const int j = target & 7;
;             u32x4 w; w.x = (hit && (j >> 1) == 0) ? ((j & 1) ? 0x3F800000u : 0x00003F80u) : 0u; w.y = (hit && (j >> 1) == 1) ? ((j & 1) ? 0x3F800000u : 0x00003F80u) : 0u;
;             w.z = (hit && (j >> 1) == 2) ? ((j & 1) ? 0x3F800000u : 0x00003F80u) : 0u; w.w = (hit && (j >> 1) == 3) ? ((j & 1) ? 0x3F800000u : 0x00003F80u) : 0u;
;             qf[s] = __builtin_bit_cast(bf16x8, w); }
;     }
;     const bf16_t* Kb = MX + tok0 * MXW + C_RK + qc;
;     const bf16_t* Vb = VT + (size_t)(hh * 256) * VTP + tok0;
;     const bf16_t* Sb = ST + ((size_t)((b * 4 + hh) * 8) << 16);
;     const int kt0 = 4 * qt, NT = mode ? 4 : (4 + (qt > 0 ? 2 : 0) + (qt < 7 ? 2 : 0));
;     ...
;     const int kA = r * 256 + 16 * (h ^ (r & 1)), sx32 = ((r & 15) >> 1) * 32;
;     const int vA = r * 128, mv16 = (((r >> 1) & 7) * 16) ^ (h * 16);
;     const LAS float* tab = (const LAS float*)(lds + RTAB_OFF);
;     f32x16 z[8];
; #pragma unroll
;     for (int d = 0; d < 8; ++d)
; #pragma unroll
;         for (int i = 0; i < 16; ++i) z[d][i] = 0.f;
;     RET_ISSUE(0, 0); RET_ISSUE(1, 1);
.LBB0_157:
	s_or_b64 exec, exec, s[4:5]
	s_mov_b32 s11, s63
	s_lshl_b64 s[4:5], s[10:11], 1
	s_add_u32 s14, s55, s4
	s_waitcnt lgkmcnt(0)
	s_barrier
	v_mbcnt_lo_u32_b32 v6, -1, 0
	v_mbcnt_hi_u32_b32 v6, -1, v6
	s_addc_u32 s15, s60, s5
	v_and_b32_e32 v7, 31, v6
	s_lshr_b32 s28, s72, 5
	v_or_b32_e32 v0, s47, v7
	s_lshl_b32 s4, s72, 4
	s_lshl_b32 s5, s72, 3
	s_lshl_b32 s62, s28, 11
	v_ashrrev_i32_e32 v1, 31, v0
	s_and_b32 s4, s4, 0x100
	s_and_b32 s5, s5, 64
	v_lshl_add_u64 v[2:3], v[0:1], 0, s[62:63]
	v_mov_b64_e32 v[4:5], s[6:7]
	s_or_b32 s11, s4, s5
	v_mad_u64_u32 v[4:5], s[4:5], v2, s50, v[4:5]
	v_mad_i32_i24 v5, v3, s50, v5
	s_lshl_b32 s4, s11, 1
	s_mov_b32 s5, s63
	v_lshrrev_b32_e32 v8, 5, v6
	v_bfe_u32 v9, v6, 5, 1
	v_lshl_add_u64 v[2:3], v[4:5], 0, s[4:5]
	s_mul_i32 s5, s28, 0x1400000
	v_lshlrev_b32_e32 v176, 4, v9
	s_mul_hi_u32 s11, s62, 0x2800
	s_add_u32 s5, s6, s5
	v_xor_b32_e32 v1, v8, v6
	v_lshl_add_u64 v[2:3], v[2:3], 0, v[176:177]
	s_addc_u32 s29, s7, s11
	s_lshl_b32 s11, s28, 22
	v_readlane_b32 s22, v254, 53
	v_lshlrev_b32_e32 v1, 4, v1
	flat_load_dwordx4 v[178:181], v[2:3]
	flat_load_dwordx4 v[182:185], v[2:3] offset:32
	flat_load_dwordx4 v[186:189], v[2:3] offset:64
	flat_load_dwordx4 v[190:193], v[2:3] offset:96
	flat_load_dwordx4 v[194:197], v[2:3] offset:256
	flat_load_dwordx4 v[198:201], v[2:3] offset:288
	flat_load_dwordx4 v[202:205], v[2:3] offset:320
	flat_load_dwordx4 v[206:209], v[2:3] offset:352
	s_or_b32 s11, s11, s22
	v_lshlrev_b32_e32 v4, 4, v6
	v_lshlrev_b32_e32 v5, 3, v6
	v_and_b32_e32 v215, 16, v1
	v_mbcnt_lo_u32_b32 v1, -1, 0
	v_mbcnt_hi_u32_b32 v1, -1, v1
	s_add_u32 s11, s3, s11
	v_ashrrev_i32_e32 v6, 4, v1
	v_add_u32_e32 v2, s24, v6
	s_addc_u32 s73, s17, 0
	v_xor_b32_e32 v3, v2, v1
	s_add_u32 s74, s5, s4
	v_lshlrev_b32_e32 v8, 4, v3
	v_lshlrev_b32_e32 v3, 3, v3
	s_addc_u32 s75, s29, 0
	v_readlane_b32 s4, v254, 6
	v_mul_u32_u24_e32 v2, s54, v2
	v_and_b32_e32 v8, 0x80, v8
	v_and_b32_e32 v3, 56, v3
	s_add_u32 s4, s74, s4
	v_or3_b32 v2, v8, v2, v3
	s_addc_u32 s5, s75, 0
	v_lshlrev_b32_e32 v2, 1, v2
	v_mov_b32_e32 v3, v177
	v_lshl_add_u64 v[2:3], s[4:5], 0, v[2:3]
	s_mov_b32 m0, s33
	v_lshl_add_u64 v[2:3], v[2:3], 0, s[64:65]
	global_load_lds_dwordx4 v[2:3], off
	v_add_u32_e32 v2, s34, v6
	v_xor_b32_e32 v3, v2, v1
	v_lshlrev_b32_e32 v6, 4, v3
	v_lshlrev_b32_e32 v3, 3, v3
	v_mul_u32_u24_e32 v2, s54, v2
	v_and_b32_e32 v6, 0x80, v6
	v_and_b32_e32 v3, 56, v3
	v_or3_b32 v2, v6, v2, v3
	v_lshlrev_b32_e32 v2, 1, v2
	v_mov_b32_e32 v3, v177
	v_lshl_add_u64 v[2:3], s[4:5], 0, v[2:3]
	s_add_i32 s29, s35, 0
	v_lshl_add_u64 v[2:3], v[2:3], 0, s[64:65]
	s_mov_b32 m0, s29
	s_lshl_b32 s4, s28, 12
	global_load_lds_dwordx4 v[2:3], off
	v_ashrrev_i32_e32 v2, 3, v1
	v_lshrrev_b32_e32 v6, 1, v2
	s_add_u32 s28, s48, s4
	v_add_u32_e32 v3, s19, v2
	v_xor_b32_e32 v6, v6, v1
	s_addc_u32 s30, s49, 0
	v_readlane_b32 s4, v254, 40
	v_mul_u32_u24_e32 v3, s0, v3
	v_lshlrev_b32_e32 v6, 3, v6
	s_add_u32 s4, s28, s4
	v_and_or_b32 v3, v6, 56, v3
	s_addc_u32 s5, s30, 0
	v_lshlrev_b32_e32 v3, 1, v3
	s_mov_b32 m0, s71
	s_add_i32 s31, s38, 0
	global_load_lds_dwordx4 v3, s[4:5]
	v_add_u32_e32 v3, s37, v2
	v_lshrrev_b32_e32 v6, 1, v3
	v_xor_b32_e32 v6, v6, v1
	v_mul_u32_u24_e32 v3, s0, v3
	v_lshlrev_b32_e32 v6, 3, v6
	v_and_or_b32 v3, v6, 56, v3
	v_lshlrev_b32_e32 v3, 1, v3
	s_add_i32 m0, s31, 0x4000
	s_add_i32 s31, s40, 0
	global_load_lds_dwordx4 v3, s[4:5]
	v_add_u32_e32 v3, s39, v2
	v_lshrrev_b32_e32 v6, 1, v3
	v_xor_b32_e32 v6, v6, v1
	v_mul_u32_u24_e32 v3, s0, v3
	v_lshlrev_b32_e32 v6, 3, v6
	v_and_or_b32 v3, v6, 56, v3
	v_lshlrev_b32_e32 v3, 1, v3
	s_add_i32 m0, s31, 0x4000
	v_add_u32_e32 v2, s41, v2
	global_load_lds_dwordx4 v3, s[4:5]
	v_lshrrev_b32_e32 v3, 1, v2
	v_xor_b32_e32 v1, v3, v1
	v_mul_u32_u24_e32 v2, s0, v2
	v_lshlrev_b32_e32 v1, 3, v1
	v_and_or_b32 v1, v1, 56, v2
	s_add_i32 s31, s43, 0
	v_lshlrev_b32_e32 v1, 1, v1
	s_add_i32 m0, s31, 0x4000
	v_subrev_u32_e32 v0, s57, v0
	global_load_lds_dwordx4 v1, s[4:5]
	v_mbcnt_lo_u32_b32 v1, -1, 0
	v_mbcnt_hi_u32_b32 v1, -1, v1
	v_readlane_b32 s4, v254, 7
	v_ashrrev_i32_e32 v6, 4, v1
	v_add_u32_e32 v2, s24, v6
	v_xor_b32_e32 v3, v2, v1
	v_lshlrev_b32_e32 v8, 4, v3
	v_lshlrev_b32_e32 v3, 3, v3
	v_mul_u32_u24_e32 v2, s54, v2
	v_and_b32_e32 v8, 0x80, v8
	v_and_b32_e32 v3, 56, v3
	s_add_u32 s4, s74, s4
	v_or3_b32 v2, v8, v2, v3
	s_addc_u32 s5, s75, 0
	v_lshlrev_b32_e32 v2, 1, v2
	v_mov_b32_e32 v3, v177
	v_lshl_add_u64 v[2:3], s[4:5], 0, v[2:3]
	v_lshl_add_u64 v[2:3], v[2:3], 0, s[64:65]
	s_add_i32 m0, s33, 0xc000
	v_bitop3_b32 v218, v176, v5, s13 bitop3:0x78
	global_load_lds_dwordx4 v[2:3], off
	v_add_u32_e32 v2, s34, v6
	v_xor_b32_e32 v3, v2, v1
	v_lshlrev_b32_e32 v6, 4, v3
	v_lshlrev_b32_e32 v3, 3, v3
	v_mul_u32_u24_e32 v2, s54, v2
	v_and_b32_e32 v6, 0x80, v6
	v_and_b32_e32 v3, 56, v3
	v_or3_b32 v2, v6, v2, v3
	v_lshlrev_b32_e32 v2, 1, v2
	v_mov_b32_e32 v3, v177
	v_lshl_add_u64 v[2:3], s[4:5], 0, v[2:3]
	v_lshl_add_u64 v[2:3], v[2:3], 0, s[64:65]
	s_add_i32 m0, s29, 0xc000
	v_readlane_b32 s4, v254, 8
	global_load_lds_dwordx4 v[2:3], off
	v_ashrrev_i32_e32 v2, 3, v1
; #define LAS __attribute__((address_space(3)))
; DI void ret_unit(LAS unsigned char* lds, bf16_t* MX, const bf16_t* VT, bf16_t* ST, int b, int hh, int qt, float lgf, float nlgb, int wave, const int mode) {
;     ...
;     const int kA = r * 256 + 16 * (h ^ (r & 1)), sx32 = ((r & 15) >> 1) * 32;
;     const int vA = r * 128, mv16 = (((r >> 1) & 7) * 16) ^ (h * 16);
;     const LAS float* tab = (const LAS float*)(lds + RTAB_OFF);
;     f32x16 z[8];
; #pragma unroll
;     for (int d = 0; d < 8; ++d)
; #pragma unroll
;         for (int i = 0; i < 16; ++i) z[d][i] = 0.f;
;     RET_ISSUE(0, 0); RET_ISSUE(1, 1);
;     int cur = 0, nx2 = 2;
;     ...
;             const float wgt = dr ? (qt < 7 ? __builtin_amdgcn_exp2f(nlgb * (float)(tq - 256 * (qt + 1))) : 0.f) : (qt > 0 ? __builtin_amdgcn_exp2f(lgf * (float)(tq - 256 * qt + 1)) : 0.f);
	v_lshrrev_b32_e32 v6, 1, v2
	v_add_u32_e32 v3, s19, v2
	v_xor_b32_e32 v6, v6, v1
	v_mul_u32_u24_e32 v3, s0, v3
	v_lshlrev_b32_e32 v6, 3, v6
	s_add_u32 s4, s28, s4
	v_and_or_b32 v3, v6, 56, v3
	s_addc_u32 s5, s30, 0
	v_lshlrev_b32_e32 v3, 1, v3
	s_add_i32 m0, s42, s36
	v_and_b32_e32 v214, 0xe0, v4
	global_load_lds_dwordx4 v3, s[4:5]
	v_add_u32_e32 v3, s37, v2
	v_lshrrev_b32_e32 v6, 1, v3
	v_xor_b32_e32 v6, v6, v1
	v_mul_u32_u24_e32 v3, s0, v3
	v_lshlrev_b32_e32 v6, 3, v6
	v_and_or_b32 v3, v6, 56, v3
	v_lshlrev_b32_e32 v3, 1, v3
	s_add_i32 m0, s42, s38
	v_lshlrev_b32_e32 v216, 7, v7
	global_load_lds_dwordx4 v3, s[4:5]
	v_add_u32_e32 v3, s39, v2
	v_lshrrev_b32_e32 v6, 1, v3
	v_xor_b32_e32 v6, v6, v1
	v_mul_u32_u24_e32 v3, s0, v3
	v_lshlrev_b32_e32 v6, 3, v6
	v_and_or_b32 v3, v6, 56, v3
	v_lshlrev_b32_e32 v3, 1, v3
	s_add_i32 m0, s42, s40
	v_add_u32_e32 v2, s41, v2
	global_load_lds_dwordx4 v3, s[4:5]
	v_lshrrev_b32_e32 v3, 1, v2
	v_xor_b32_e32 v1, v3, v1
	v_mul_u32_u24_e32 v2, s0, v2
	v_lshlrev_b32_e32 v1, 3, v1
	v_and_or_b32 v1, v1, 56, v2
	v_lshlrev_b32_e32 v1, 1, v1
	s_add_i32 m0, s42, s43
	v_add_u32_e32 v2, 0xffffff00, v0
	global_load_lds_dwordx4 v1, s[4:5]
	v_cvt_f32_i32_e32 v2, v2
	v_add_u32_e32 v0, 1, v0
	v_readlane_b32 s4, v254, 4
	v_readlane_b32 s5, v254, 5
	v_mul_f32_e32 v1, v213, v2
	v_exp_f32_e32 v1, v1
	v_cvt_f32_i32_e32 v2, v0
	v_mov_b32_e32 v0, 0
	v_lshlrev_b32_e32 v217, 8, v7
	v_cndmask_b32_e64 v219, v1, 0, s[4:5]
	s_movk_i32 s4, 0x60
	v_mul_f32_e32 v1, v212, v2
	v_bitop3_b32 v223, v4, s4, v243 bitop3:0x6c
	s_movk_i32 s4, 0x80
	v_exp_f32_e32 v220, v1
	v_bitop3_b32 v224, v4, s4, v243 bitop3:0x6c
	s_movk_i32 s4, 0xa0
	v_bitop3_b32 v225, v4, s4, v243 bitop3:0x6c
	s_movk_i32 s4, 0xc0
	v_mul_i32_i24_e32 v1, -4, v9
	v_bitop3_b32 v226, v4, s4, v243 bitop3:0x6c
	s_movk_i32 s4, 0xe0
	v_bitop3_b32 v221, v4, 32, v243 bitop3:0x6c
	v_bitop3_b32 v222, v4, 64, v243 bitop3:0x6c
	v_bitop3_b32 v227, v4, s4, v4 bitop3:0xc
	v_xor_b32_e32 v228, 32, v218
	v_xor_b32_e32 v229, 64, v218
	v_xor_b32_e32 v230, 0x60, v218
	v_add3_u32 v231, s19, v1, v7
	s_mov_b32 s77, 2
	s_mov_b32 s76, 0
	s_mov_b32 s78, 0
	s_mov_b32 s30, 0
	v_mov_b32_e32 v1, v0
	v_mov_b32_e32 v2, v0
	v_mov_b32_e32 v3, v0
	v_mov_b32_e32 v4, v0
	v_mov_b32_e32 v5, v0
	v_mov_b32_e32 v6, v0
	v_mov_b32_e32 v7, v0
	v_mov_b32_e32 v8, v0
	v_mov_b32_e32 v9, v0
	v_mov_b32_e32 v10, v0
	v_mov_b32_e32 v11, v0
	v_mov_b32_e32 v12, v0
	v_mov_b32_e32 v13, v0
	v_mov_b32_e32 v14, v0
	v_mov_b32_e32 v15, v0
	v_mov_b32_e32 v16, v0
	v_mov_b32_e32 v17, v0
	v_mov_b32_e32 v18, v0
	v_mov_b32_e32 v19, v0
	v_mov_b32_e32 v20, v0
	v_mov_b32_e32 v21, v0
	v_mov_b32_e32 v22, v0
	v_mov_b32_e32 v23, v0
	v_mov_b32_e32 v24, v0
	v_mov_b32_e32 v25, v0
	v_mov_b32_e32 v26, v0
	v_mov_b32_e32 v27, v0
	v_mov_b32_e32 v28, v0
	v_mov_b32_e32 v29, v0
	v_mov_b32_e32 v30, v0
	v_mov_b32_e32 v31, v0
	v_mov_b32_e32 v32, v0
	v_mov_b32_e32 v33, v0
	v_mov_b32_e32 v34, v0
	v_mov_b32_e32 v35, v0
	v_mov_b32_e32 v36, v0
	v_mov_b32_e32 v37, v0
	v_mov_b32_e32 v38, v0
	v_mov_b32_e32 v39, v0
	v_mov_b32_e32 v40, v0
	v_mov_b32_e32 v41, v0
	v_mov_b32_e32 v42, v0
	v_mov_b32_e32 v43, v0
	v_mov_b32_e32 v44, v0
	v_mov_b32_e32 v45, v0
	v_mov_b32_e32 v46, v0
	v_mov_b32_e32 v47, v0
	v_mov_b32_e32 v48, v0
	v_mov_b32_e32 v49, v0
	v_mov_b32_e32 v50, v0
	v_mov_b32_e32 v51, v0
	v_mov_b32_e32 v52, v0
	v_mov_b32_e32 v53, v0
	v_mov_b32_e32 v54, v0
	v_mov_b32_e32 v55, v0
	v_mov_b32_e32 v56, v0
	v_mov_b32_e32 v57, v0
	v_mov_b32_e32 v58, v0
	v_mov_b32_e32 v59, v0
	v_mov_b32_e32 v60, v0
	v_mov_b32_e32 v61, v0
	v_mov_b32_e32 v62, v0
	v_mov_b32_e32 v63, v0
	v_mov_b32_e32 v64, v0
	v_mov_b32_e32 v65, v0
	v_mov_b32_e32 v66, v0
	v_mov_b32_e32 v67, v0
	v_mov_b32_e32 v68, v0
	v_mov_b32_e32 v69, v0
	v_mov_b32_e32 v70, v0
	v_mov_b32_e32 v71, v0
	v_mov_b32_e32 v72, v0
	v_mov_b32_e32 v73, v0
	v_mov_b32_e32 v74, v0
	v_mov_b32_e32 v75, v0
	v_mov_b32_e32 v76, v0
	v_mov_b32_e32 v77, v0
	v_mov_b32_e32 v78, v0
	v_mov_b32_e32 v79, v0
	v_mov_b32_e32 v80, v0
	v_mov_b32_e32 v81, v0
	v_mov_b32_e32 v82, v0
	v_mov_b32_e32 v83, v0
	v_mov_b32_e32 v84, v0
	v_mov_b32_e32 v85, v0
	v_mov_b32_e32 v86, v0
	v_mov_b32_e32 v87, v0
	v_mov_b32_e32 v88, v0
	v_mov_b32_e32 v89, v0
	v_mov_b32_e32 v90, v0
	v_mov_b32_e32 v91, v0
	v_mov_b32_e32 v92, v0
	v_mov_b32_e32 v93, v0
	v_mov_b32_e32 v94, v0
	v_mov_b32_e32 v95, v0
	v_mov_b32_e32 v96, v0
	v_mov_b32_e32 v97, v0
	v_mov_b32_e32 v98, v0
	v_mov_b32_e32 v99, v0
	v_mov_b32_e32 v100, v0
	v_mov_b32_e32 v101, v0
	v_mov_b32_e32 v102, v0
	v_mov_b32_e32 v103, v0
	v_mov_b32_e32 v104, v0
	v_mov_b32_e32 v105, v0
	v_mov_b32_e32 v106, v0
	v_mov_b32_e32 v107, v0
	v_mov_b32_e32 v108, v0
	v_mov_b32_e32 v109, v0
	v_mov_b32_e32 v110, v0
	v_mov_b32_e32 v111, v0
	v_mov_b32_e32 v112, v0
	v_mov_b32_e32 v113, v0
	v_mov_b32_e32 v114, v0
	v_mov_b32_e32 v115, v0
	v_mov_b32_e32 v116, v0
	v_mov_b32_e32 v117, v0
	v_mov_b32_e32 v118, v0
	v_mov_b32_e32 v119, v0
	v_mov_b32_e32 v120, v0
	v_mov_b32_e32 v121, v0
	v_mov_b32_e32 v122, v0
	v_mov_b32_e32 v123, v0
	v_mov_b32_e32 v124, v0
	v_mov_b32_e32 v125, v0
	v_mov_b32_e32 v126, v0
	v_mov_b32_e32 v127, v0
	s_waitcnt vmcnt(0)
	s_branch .LBB0_160

; #define LAS __attribute__((address_space(3)))
; DI void ret_unit(LAS unsigned char* lds, bf16_t* MX, const bf16_t* VT, bf16_t* ST, int b, int hh, int qt, float lgf, float nlgb, int wave, const int mode) {
;     ...
;     const int kA = r * 256 + 16 * (h ^ (r & 1)), sx32 = ((r & 15) >> 1) * 32;
;     const int vA = r * 128, mv16 = (((r >> 1) & 7) * 16) ^ (h * 16);
;     const LAS float* tab = (const LAS float*)(lds + RTAB_OFF);
;     f32x16 z[8];
; #pragma unroll
;     for (int d = 0; d < 8; ++d)
; #pragma unroll
;         for (int i = 0; i < 16; ++i) z[d][i] = 0.f;
;     RET_ISSUE(0, 0); RET_ISSUE(1, 1);
;     int cur = 0, nx2 = 2;
; #pragma unroll 1
;     for (int t = 0; t < NT; ++t) {
;         if (t + 1 < NT) asm volatile("s_waitcnt vmcnt(6)" ::: "memory");
;         else asm volatile("s_waitcnt vmcnt(0)" ::: "memory");
;         __builtin_amdgcn_s_barrier();
;         asm volatile("" ::: "memory");
;         if (t + 2 < NT) RET_ISSUE(t + 2, nx2);
.LBB0_164:
	s_barrier
	s_add_i32 s4, s30, 2
	s_cmp_ge_u32 s4, s53
	s_cbranch_scc1 .LBB0_170
	v_mbcnt_lo_u32_b32 v128, -1, 0
	v_mbcnt_hi_u32_b32 v128, -1, v128
	s_cmp_lt_u32 s30, 2
	v_ashrrev_i32_e32 v129, 4, v128
	v_add_u32_e32 v130, s24, v129
	s_cselect_b32 s4, s4, 0
	v_xor_b32_e32 v131, v130, v128
	s_add_i32 s4, s4, s56
	v_lshlrev_b32_e32 v132, 4, v131
	v_lshlrev_b32_e32 v131, 3, v131
	s_mul_hi_u32 s5, s4, 0xa0000
	s_mul_i32 s4, s4, 0xa0000
	v_mul_u32_u24_e32 v130, s54, v130
	v_and_b32_e32 v132, 0x80, v132
	v_and_b32_e32 v131, 56, v131
	s_add_u32 s4, s74, s4
	v_or3_b32 v130, v132, v130, v131
	s_addc_u32 s5, s75, s5
	s_mul_i32 s28, s77, 0xc000
	v_lshlrev_b32_e32 v176, 1, v130
	s_add_i32 s31, s28, 0
	v_lshl_add_u64 v[130:131], s[4:5], 0, v[176:177]
	s_add_i32 m0, s31, s25
	v_lshl_add_u64 v[130:131], v[130:131], 0, s[64:65]
	v_add_u32_e32 v129, s34, v129
	global_load_lds_dwordx4 v[130:131], off
	v_xor_b32_e32 v130, v129, v128
	v_lshlrev_b32_e32 v131, 4, v130
	v_lshlrev_b32_e32 v130, 3, v130
	v_mul_u32_u24_e32 v129, s54, v129
	v_and_b32_e32 v131, 0x80, v131
	v_and_b32_e32 v130, 56, v130
	v_or3_b32 v129, v131, v129, v130
	v_lshlrev_b32_e32 v176, 1, v129
	s_add_i32 s28, s31, s35
	v_lshl_add_u64 v[130:131], s[4:5], 0, v[176:177]
	v_lshl_add_u64 v[130:131], v[130:131], 0, s[64:65]
	s_mov_b32 m0, s28
	v_ashrrev_i32_e32 v132, 3, v128
	global_load_lds_dwordx4 v[130:131], off
	s_cmp_gt_u32 s30, 1
	s_mov_b64 s[28:29], -1
	v_lshrrev_b32_e32 v133, 1, v132
	v_add_u32_e32 v131, s37, v132
	v_add_u32_e32 v130, s39, v132
	v_add_u32_e32 v129, s41, v132
	s_cbranch_scc0 .LBB0_167
	s_add_i32 s4, s30, -2
	s_lshr_b32 s28, s4, 1
	s_and_b64 s[4:5], s[90:91], exec
	s_cselect_b32 s4, 1, s28
	s_cmp_eq_u32 s4, 0
	s_cselect_b32 s5, s92, s89
	s_lshl_b32 s5, s5, 17
	s_add_u32 s5, s11, s5
	s_addc_u32 s28, s73, 0
	s_lshl_b32 s4, s4, 8
	s_add_u32 s4, s5, s4
	s_addc_u32 s5, s28, 0
	s_and_b32 s28, s76, 64
	s_lshl_b32 s28, s28, 1
	s_add_u32 s4, s4, s28
	v_xor_b32_e32 v134, v133, v128
	s_addc_u32 s5, s5, 0
	v_add_lshl_u32 v135, v132, s19, 9
	v_lshlrev_b32_e32 v134, 4, v134
	s_add_i32 s28, s31, s36
	v_and_or_b32 v134, v134, s13, v135
	s_add_i32 m0, s28, 0x4000
	v_lshlrev_b32_e32 v135, 9, v131
	global_load_lds_dwordx4 v134, s[4:5]
	v_lshrrev_b32_e32 v134, 1, v131
	v_xor_b32_e32 v134, v134, v128
	v_lshlrev_b32_e32 v134, 4, v134
	s_add_i32 s28, s31, s38
	v_and_or_b32 v134, v134, s13, v135
	s_add_i32 m0, s28, 0x4000
	v_lshlrev_b32_e32 v135, 9, v130
	global_load_lds_dwordx4 v134, s[4:5]
	v_lshrrev_b32_e32 v134, 1, v130
	v_xor_b32_e32 v134, v134, v128
	v_lshlrev_b32_e32 v134, 4, v134
	s_add_i32 s28, s31, s40
	v_and_or_b32 v134, v134, s13, v135
	s_add_i32 m0, s28, 0x4000
	v_lshlrev_b32_e32 v135, 9, v129
	global_load_lds_dwordx4 v134, s[4:5]
	v_lshrrev_b32_e32 v134, 1, v129
	v_xor_b32_e32 v134, v134, v128
	v_lshlrev_b32_e32 v134, 4, v134
	v_and_or_b32 v134, v134, s13, v135
	s_mov_b64 s[28:29], 0
.LBB0_167:
	s_andn2_b64 vcc, exec, s[28:29]
	s_cbranch_vccnz .LBB0_169
	v_xor_b32_e32 v133, v133, v128
	v_lshlrev_b32_e32 v133, 3, v133
	v_mul_u32_u24_e32 v132, s0, v132
	v_lshrrev_b32_e32 v131, 1, v131
	v_and_b32_e32 v133, 56, v133
	v_add_u32_e32 v134, s61, v132
	s_add_i32 s4, s31, s36
	v_xor_b32_e32 v131, v131, v128
	v_add_lshl_u32 v133, v134, v133, 1
	s_add_i32 m0, s4, 0x4000
	v_lshlrev_b32_e32 v131, 3, v131
	v_lshrrev_b32_e32 v130, 1, v130
	global_load_lds_dwordx4 v133, s[14:15]
	v_and_b32_e32 v131, 56, v131
	v_add_u32_e32 v133, s69, v132
	s_add_i32 s4, s31, s38
	v_xor_b32_e32 v130, v130, v128
	v_add_lshl_u32 v131, v133, v131, 1
	s_add_i32 m0, s4, 0x4000
	v_lshlrev_b32_e32 v130, 3, v130
	global_load_lds_dwordx4 v131, s[14:15]
	v_and_b32_e32 v130, 56, v130
	v_add_u32_e32 v131, s68, v132
	s_add_i32 s4, s31, s40
	v_add_lshl_u32 v130, v131, v130, 1
	s_add_i32 m0, s4, 0x4000
	s_mov_b64 s[4:5], s[14:15]
	global_load_lds_dwordx4 v130, s[14:15]
	v_lshrrev_b32_e32 v130, 1, v129
	v_xor_b32_e32 v128, v130, v128
	v_mul_u32_u24_e32 v129, s0, v129
	v_lshlrev_b32_e32 v128, 3, v128
	v_and_or_b32 v128, v128, 56, v129
	v_lshlrev_b32_e32 v134, 1, v128
